# phase 12 K-loop: first P-operand fragment reads of each K-tile moved to the previous tile's last memory interval (LDS reads per interval 12/4/8/0 -> 8/4/8/4)
# speedup vs baseline: 1.0043x; 1.0043x over previous
; #define PG8_STAGE(bufoff, gbase, voff) do { _Pragma("unroll") for (int _i = 0; _i < 2; ++_i) \
;         __builtin_amdgcn_global_load_lds((const unsigned*)((const char*)(gbase) + (voff)[_i]), (LAS unsigned*)(lds + (bufoff) + ldsw + _i * 8192), 16, 0, 0); } while (0)
; #define PG8_LDA(dst, b, h) do { _Pragma("unroll") for (int m = 0; m < 4; ++m) _Pragma("unroll") for (int k = 0; k < 2; ++k) dst[m][k] = *(const LAS bf16x8*)(lds + PG8_SA(b, h) + aoff + m * 2048 + k * 1024); } while (0)
; #define PG8_LDB(dst, b, h) do { _Pragma("unroll") for (int n = 0; n < 2; ++n) _Pragma("unroll") for (int k = 0; k < 2; ++k) dst[n][k] = *(const LAS bf16x8*)(lds + PG8_SB(b, h) + boff + n * 2048 + k * 1024); } while (0)
; #define PG8_MMA(ai, bj, At, Bt) do { __builtin_amdgcn_s_setprio(1); _Pragma("unroll") for (int m = 0; m < 4; ++m) _Pragma("unroll") for (int n = 0; n < 2; ++n) _Pragma("unroll") for (int k = 0; k < 2; ++k) \
;         acc[ai][bj][m][n] = __builtin_amdgcn_mfma_f32_16x16x32_bf16(Bt[n][k], At[m][k], acc[ai][bj][m][n], 0, 0, 0); __builtin_amdgcn_s_setprio(0); } while (0)
; #define PG8_WAIT_L(n) asm volatile("s_waitcnt lgkmcnt(" #n ")" ::: "memory")
; #define PG8_BAR __builtin_amdgcn_s_barrier()
; #define PG8_SCHED __builtin_amdgcn_sched_barrier(0)
; template <class Epi, class Sched>
; __device__ __forceinline__ void gemm_phase(LAS unsigned char* lds, const Gemm g, const Sched& S, const Epi& E) {
;     ...
;         for (int t = 0; t < nt; t += 2) {
;             const bool last = (t == nt - 2);
;             const char* a1 = cA + (size_t)(t + 1) * kstep;
;             const char* a2 = last ? nA : cA + (size_t)(t + 2) * kstep; const char* b2 = last ? nB : cB + (size_t)(t + 2) * kstep;
;             const char* a3 = a2 + kstep; const char* b3 = b2 + kstep;
;             PG8_LDB(B0, 0, 0); PG8_SCHED; PG8_LDA(At, 0, 0); PG8_STAGE(PG8_SA(1, 1), a1 + hstepA, voffA);
;             PG8_WAIT_L(8); PG8_BAR; PG8_WAIT_L(0); PG8_MMA(0, 0, At, B0); PG8_BAR; PG8_SCHED;
;     ...
; #pragma unroll
;         for (int a = 0; a < 2; ++a)
; #pragma unroll
;             for (int b = 0; b < 2; ++b)
; #pragma unroll
;                 for (int m = 0; m < 4; ++m)
; #pragma unroll
;                     for (int n = 0; n < 2; ++n) acc[a][b][m][n] = (f32x4){0.f, 0.f, 0.f, 0.f};
;         cur = nxt; cA = nA; cB = nB; ++ui;
.LBB0_1842:
	s_ashr_i32 s15, s14, 31
	v_cmp_lt_i64_e32 vcc, s[16:17], v[140:141]
	s_lshl_b64 s[16:17], s[14:15], 20
	s_add_u32 s16, s28, s16
	s_addc_u32 s17, s29, s17
	s_and_b64 s[18:19], vcc, exec
	s_cselect_b32 s15, s17, s23
	s_cselect_b32 s48, s16, s22
	s_ashr_i32 s13, s12, 31
	s_lshl_b64 s[18:19], s[12:13], 20
	s_add_u32 s18, s30, s18
	s_addc_u32 s19, s31, s19
	s_and_b64 s[26:27], vcc, exec
	s_cselect_b32 s13, s19, s25
	s_cselect_b32 s49, s18, s24
	s_add_u32 s22, s22, 0x80080
	s_addc_u32 s23, s23, 0
	s_add_u32 s50, s24, 0x100
	v_mov_b32_e32 v0, 0
	s_addc_u32 s51, s25, 0
	s_mov_b32 s52, -2
	v_mov_b32_e32 v1, v0
	v_mov_b32_e32 v2, v0
	v_mov_b32_e32 v3, v0
	v_mov_b32_e32 v8, v0
	v_mov_b32_e32 v9, v0
	v_mov_b32_e32 v10, v0
	v_mov_b32_e32 v11, v0
	v_mov_b32_e32 v16, v0
	v_mov_b32_e32 v17, v0
	v_mov_b32_e32 v18, v0
	v_mov_b32_e32 v19, v0
	v_mov_b32_e32 v24, v0
	v_mov_b32_e32 v25, v0
	v_mov_b32_e32 v26, v0
	v_mov_b32_e32 v27, v0
	v_mov_b32_e32 v32, v0
	v_mov_b32_e32 v33, v0
	v_mov_b32_e32 v34, v0
	v_mov_b32_e32 v35, v0
	v_mov_b32_e32 v40, v0
	v_mov_b32_e32 v41, v0
	v_mov_b32_e32 v42, v0
	v_mov_b32_e32 v43, v0
	v_mov_b32_e32 v48, v0
	v_mov_b32_e32 v49, v0
	v_mov_b32_e32 v50, v0
	v_mov_b32_e32 v51, v0
	v_mov_b32_e32 v56, v0
	v_mov_b32_e32 v57, v0
	v_mov_b32_e32 v58, v0
	v_mov_b32_e32 v59, v0
	v_mov_b32_e32 v4, v0
	v_mov_b32_e32 v5, v0
	v_mov_b32_e32 v6, v0
	v_mov_b32_e32 v7, v0
	v_mov_b32_e32 v12, v0
	v_mov_b32_e32 v13, v0
	v_mov_b32_e32 v14, v0
	v_mov_b32_e32 v15, v0
	v_mov_b32_e32 v20, v0
	v_mov_b32_e32 v21, v0
	v_mov_b32_e32 v22, v0
	v_mov_b32_e32 v23, v0
	v_mov_b32_e32 v28, v0
	v_mov_b32_e32 v29, v0
	v_mov_b32_e32 v30, v0
	v_mov_b32_e32 v31, v0
	v_mov_b32_e32 v36, v0
	v_mov_b32_e32 v37, v0
	v_mov_b32_e32 v38, v0
	v_mov_b32_e32 v39, v0
	v_mov_b32_e32 v44, v0
	v_mov_b32_e32 v45, v0
	v_mov_b32_e32 v46, v0
	v_mov_b32_e32 v47, v0
	v_mov_b32_e32 v52, v0
	v_mov_b32_e32 v53, v0
	v_mov_b32_e32 v54, v0
	v_mov_b32_e32 v55, v0
	v_mov_b32_e32 v60, v0
	v_mov_b32_e32 v61, v0
	v_mov_b32_e32 v62, v0
	v_mov_b32_e32 v63, v0
	v_mov_b32_e32 v64, v0
	v_mov_b32_e32 v65, v0
	v_mov_b32_e32 v66, v0
	v_mov_b32_e32 v67, v0
	v_mov_b32_e32 v72, v0
	v_mov_b32_e32 v73, v0
	v_mov_b32_e32 v74, v0
	v_mov_b32_e32 v75, v0
	v_mov_b32_e32 v80, v0
	v_mov_b32_e32 v81, v0
	v_mov_b32_e32 v82, v0
	v_mov_b32_e32 v83, v0
	v_mov_b32_e32 v88, v0
	v_mov_b32_e32 v89, v0
	v_mov_b32_e32 v90, v0
	v_mov_b32_e32 v91, v0
	v_mov_b32_e32 v96, v0
	v_mov_b32_e32 v97, v0
	v_mov_b32_e32 v98, v0
	v_mov_b32_e32 v99, v0
	v_mov_b32_e32 v104, v0
	v_mov_b32_e32 v105, v0
	v_mov_b32_e32 v106, v0
	v_mov_b32_e32 v107, v0
	v_mov_b32_e32 v112, v0
	v_mov_b32_e32 v113, v0
	v_mov_b32_e32 v114, v0
	v_mov_b32_e32 v115, v0
	v_mov_b32_e32 v120, v0
	v_mov_b32_e32 v121, v0
	v_mov_b32_e32 v122, v0
	v_mov_b32_e32 v123, v0
	v_mov_b32_e32 v68, v0
	v_mov_b32_e32 v69, v0
	v_mov_b32_e32 v70, v0
	v_mov_b32_e32 v71, v0
	v_mov_b32_e32 v76, v0
	v_mov_b32_e32 v77, v0
	v_mov_b32_e32 v78, v0
	v_mov_b32_e32 v79, v0
	v_mov_b32_e32 v84, v0
	v_mov_b32_e32 v85, v0
	v_mov_b32_e32 v86, v0
	v_mov_b32_e32 v87, v0
	v_mov_b32_e32 v92, v0
	v_mov_b32_e32 v93, v0
	v_mov_b32_e32 v94, v0
	v_mov_b32_e32 v95, v0
	v_mov_b32_e32 v100, v0
	v_mov_b32_e32 v101, v0
	v_mov_b32_e32 v102, v0
	v_mov_b32_e32 v103, v0
	v_mov_b32_e32 v108, v0
	v_mov_b32_e32 v109, v0
	v_mov_b32_e32 v110, v0
	v_mov_b32_e32 v111, v0
	v_mov_b32_e32 v116, v0
	v_mov_b32_e32 v117, v0
	v_mov_b32_e32 v118, v0
	v_mov_b32_e32 v119, v0
	v_mov_b32_e32 v124, v0
	v_mov_b32_e32 v125, v0
	v_mov_b32_e32 v126, v0
	v_mov_b32_e32 v127, v0
	ds_read_b128 v[150:153], v147
	ds_read_b128 v[154:157], v147 offset:1024
	ds_read_b128 v[162:165], v147 offset:2048
	ds_read_b128 v[166:169], v147 offset:3072
.LBB0_1843:
	s_add_u32 s24, s22, 0xfff80080
	s_addc_u32 s25, s23, -1
	s_cmp_eq_u32 s52, 28
	s_cselect_b32 s27, s15, s25
	s_cselect_b32 s26, s48, s24
	s_cselect_b32 s25, s13, s51
	s_cselect_b32 s24, s49, s50
	v_lshl_add_u64 v[158:159], s[22:23], 0, v[136:137]
	s_add_i32 m0, s21, 0xc000
	ds_read_b128 v[170:173], v148
	ds_read_b128 v[174:177], v148 offset:1024
	ds_read_b128 v[178:181], v148 offset:2048
	ds_read_b128 v[186:189], v148 offset:3072
	ds_read_b128 v[190:193], v148 offset:4096
	ds_read_b128 v[194:197], v148 offset:5120
	ds_read_b128 v[198:201], v148 offset:6144
	ds_read_b128 v[202:205], v148 offset:7168
	global_load_lds_dwordx4 v[158:159], off
	v_lshl_add_u64 v[158:159], s[22:23], 0, v[138:139]
	s_add_i32 m0, s21, 0xe000
	s_nop 0
	global_load_lds_dwordx4 v[158:159], off
	s_waitcnt lgkmcnt(8)
	s_barrier
	s_waitcnt lgkmcnt(0)
	s_setprio 1
	s_waitcnt lgkmcnt(0)
	v_mfma_f32_16x16x32_bf16 v[124:127], v[150:153], v[170:173], v[124:127]
	v_mfma_f32_16x16x32_bf16 v[116:119], v[162:165], v[170:173], v[116:119]
	v_mfma_f32_16x16x32_bf16 v[108:111], v[150:153], v[178:181], v[108:111]
	v_mfma_f32_16x16x32_bf16 v[100:103], v[162:165], v[178:181], v[100:103]
	v_mfma_f32_16x16x32_bf16 v[92:95], v[150:153], v[190:193], v[92:95]
	v_mfma_f32_16x16x32_bf16 v[84:87], v[162:165], v[190:193], v[84:87]
	v_mfma_f32_16x16x32_bf16 v[76:79], v[150:153], v[198:201], v[76:79]
	v_mfma_f32_16x16x32_bf16 v[68:71], v[162:165], v[198:201], v[68:71]
	v_mfma_f32_16x16x32_bf16 v[124:127], v[154:157], v[174:177], v[124:127]
	v_mfma_f32_16x16x32_bf16 v[116:119], v[166:169], v[174:177], v[116:119]
	v_mfma_f32_16x16x32_bf16 v[108:111], v[154:157], v[186:189], v[108:111]
	v_mfma_f32_16x16x32_bf16 v[100:103], v[166:169], v[186:189], v[100:103]
	v_mfma_f32_16x16x32_bf16 v[92:95], v[154:157], v[194:197], v[92:95]
	v_mfma_f32_16x16x32_bf16 v[84:87], v[166:169], v[194:197], v[84:87]
	v_mfma_f32_16x16x32_bf16 v[76:79], v[154:157], v[202:205], v[76:79]
	v_mfma_f32_16x16x32_bf16 v[68:71], v[166:169], v[202:205], v[68:71]
	s_setprio 0
	s_barrier
; #define PG8_STAGE(bufoff, gbase, voff) do { _Pragma("unroll") for (int _i = 0; _i < 2; ++_i) \
;         __builtin_amdgcn_global_load_lds((const unsigned*)((const char*)(gbase) + (voff)[_i]), (LAS unsigned*)(lds + (bufoff) + ldsw + _i * 8192), 16, 0, 0); } while (0)
; #define PG8_LDA(dst, b, h) do { _Pragma("unroll") for (int m = 0; m < 4; ++m) _Pragma("unroll") for (int k = 0; k < 2; ++k) dst[m][k] = *(const LAS bf16x8*)(lds + PG8_SA(b, h) + aoff + m * 2048 + k * 1024); } while (0)
; #define PG8_LDB(dst, b, h) do { _Pragma("unroll") for (int n = 0; n < 2; ++n) _Pragma("unroll") for (int k = 0; k < 2; ++k) dst[n][k] = *(const LAS bf16x8*)(lds + PG8_SB(b, h) + boff + n * 2048 + k * 1024); } while (0)
; #define PG8_MMA(ai, bj, At, Bt) do { __builtin_amdgcn_s_setprio(1); _Pragma("unroll") for (int m = 0; m < 4; ++m) _Pragma("unroll") for (int n = 0; n < 2; ++n) _Pragma("unroll") for (int k = 0; k < 2; ++k) \
;         acc[ai][bj][m][n] = __builtin_amdgcn_mfma_f32_16x16x32_bf16(Bt[n][k], At[m][k], acc[ai][bj][m][n], 0, 0, 0); __builtin_amdgcn_s_setprio(0); } while (0)
; #define PG8_WAIT_V(n) asm volatile("s_waitcnt vmcnt(" #n ")" ::: "memory")
; #define PG8_WAIT_L(n) asm volatile("s_waitcnt lgkmcnt(" #n ")" ::: "memory")
; #define PG8_BAR __builtin_amdgcn_s_barrier()
; #define PG8_SCHED __builtin_amdgcn_sched_barrier(0)
; template <class Epi, class Sched>
; __device__ __forceinline__ void gemm_phase(LAS unsigned char* lds, const Gemm g, const Sched& S, const Epi& E) {
;     ...
;             PG8_LDB(B1, 0, 1); PG8_STAGE(PG8_SB(0, 0), b2, voffB);
;             PG8_BAR; PG8_WAIT_L(0); if constexpr (!Epi::DIAG) PG8_MMA(0, 1, At, B1); PG8_BAR;
;             PG8_LDA(At, 0, 1); PG8_STAGE(PG8_SA(0, 0), a2, voffA);
;             PG8_BAR; PG8_WAIT_L(0); if constexpr (!Epi::DIAG) PG8_MMA(1, 0, At, B0); PG8_BAR; PG8_SCHED;
;             PG8_STAGE(PG8_SB(0, 1), b2 + hstepB, voffB);
;             PG8_WAIT_V(6); PG8_BAR; PG8_MMA(1, 1, At, B1); PG8_BAR;
;             PG8_LDB(B0, 1, 0); PG8_SCHED; PG8_LDA(At, 1, 0); PG8_STAGE(PG8_SA(0, 1), a2 + hstepA, voffA);
;             PG8_WAIT_L(8); PG8_BAR; PG8_WAIT_L(0); PG8_MMA(0, 0, At, B0); PG8_BAR; PG8_SCHED;
	s_add_i32 s53, s44, s34
	v_lshl_add_u64 v[158:159], s[24:25], 0, v[130:131]
	s_mov_b32 m0, s53
	ds_read_b128 v[206:209], v149
	ds_read_b128 v[210:213], v149 offset:1024
	ds_read_b128 v[214:217], v149 offset:2048
	ds_read_b128 v[218:221], v149 offset:3072
	global_load_lds_dwordx4 v[158:159], off
	v_lshl_add_u64 v[182:183], s[24:25], 0, v[134:135]
	s_add_i32 m0, s53, 0x2000
	s_nop 0
	global_load_lds_dwordx4 v[182:183], off
	s_barrier
	s_waitcnt lgkmcnt(0)
	s_setprio 1
	s_waitcnt lgkmcnt(0)
	v_mfma_f32_16x16x32_bf16 v[120:123], v[206:209], v[170:173], v[120:123]
	v_mfma_f32_16x16x32_bf16 v[112:115], v[214:217], v[170:173], v[112:115]
	v_mfma_f32_16x16x32_bf16 v[104:107], v[206:209], v[178:181], v[104:107]
	v_mfma_f32_16x16x32_bf16 v[96:99], v[214:217], v[178:181], v[96:99]
	v_mfma_f32_16x16x32_bf16 v[88:91], v[206:209], v[190:193], v[88:91]
	v_mfma_f32_16x16x32_bf16 v[80:83], v[214:217], v[190:193], v[80:83]
	v_mfma_f32_16x16x32_bf16 v[72:75], v[206:209], v[198:201], v[72:75]
	v_mfma_f32_16x16x32_bf16 v[64:67], v[214:217], v[198:201], v[64:67]
	v_mfma_f32_16x16x32_bf16 v[120:123], v[210:213], v[174:177], v[120:123]
	v_mfma_f32_16x16x32_bf16 v[112:115], v[218:221], v[174:177], v[112:115]
	v_mfma_f32_16x16x32_bf16 v[104:107], v[210:213], v[186:189], v[104:107]
	v_mfma_f32_16x16x32_bf16 v[96:99], v[218:221], v[186:189], v[96:99]
	v_mfma_f32_16x16x32_bf16 v[88:91], v[210:213], v[194:197], v[88:91]
	v_mfma_f32_16x16x32_bf16 v[80:83], v[218:221], v[194:197], v[80:83]
	v_mfma_f32_16x16x32_bf16 v[72:75], v[210:213], v[202:205], v[72:75]
	v_mfma_f32_16x16x32_bf16 v[64:67], v[218:221], v[202:205], v[64:67]
	s_setprio 0
	s_mov_b32 m0, s21
	v_lshl_add_u64 v[222:223], s[26:27], 0, v[128:129]
	s_barrier
	ds_read_b128 v[170:173], v148 offset:16384
	ds_read_b128 v[174:177], v148 offset:17408
	ds_read_b128 v[178:181], v148 offset:18432
	ds_read_b128 v[186:189], v148 offset:19456
	ds_read_b128 v[190:193], v148 offset:20480
	ds_read_b128 v[194:197], v148 offset:21504
	ds_read_b128 v[198:201], v148 offset:22528
	ds_read_b128 v[202:205], v148 offset:23552
	global_load_lds_dwordx4 v[222:223], off
	v_lshl_add_u64 v[224:225], s[26:27], 0, v[132:133]
	s_mov_b32 m0, s37
	s_nop 0
	global_load_lds_dwordx4 v[224:225], off
	s_waitcnt vmcnt(10)
	s_barrier
	s_waitcnt lgkmcnt(0)
	s_setprio 1
	s_waitcnt lgkmcnt(0)
	v_mfma_f32_16x16x32_bf16 v[60:63], v[150:153], v[170:173], v[60:63]
	v_mfma_f32_16x16x32_bf16 v[52:55], v[162:165], v[170:173], v[52:55]
	v_mfma_f32_16x16x32_bf16 v[44:47], v[150:153], v[178:181], v[44:47]
	v_mfma_f32_16x16x32_bf16 v[36:39], v[162:165], v[178:181], v[36:39]
	v_mfma_f32_16x16x32_bf16 v[28:31], v[150:153], v[190:193], v[28:31]
	v_mfma_f32_16x16x32_bf16 v[20:23], v[162:165], v[190:193], v[20:23]
	v_mfma_f32_16x16x32_bf16 v[12:15], v[150:153], v[198:201], v[12:15]
	v_mfma_f32_16x16x32_bf16 v[4:7], v[162:165], v[198:201], v[4:7]
	v_mfma_f32_16x16x32_bf16 v[60:63], v[154:157], v[174:177], v[60:63]
	v_mfma_f32_16x16x32_bf16 v[52:55], v[166:169], v[174:177], v[52:55]
	v_mfma_f32_16x16x32_bf16 v[44:47], v[154:157], v[186:189], v[44:47]
	v_mfma_f32_16x16x32_bf16 v[36:39], v[166:169], v[186:189], v[36:39]
	v_mfma_f32_16x16x32_bf16 v[28:31], v[154:157], v[194:197], v[28:31]
	v_mfma_f32_16x16x32_bf16 v[20:23], v[166:169], v[194:197], v[20:23]
	v_mfma_f32_16x16x32_bf16 v[12:15], v[154:157], v[202:205], v[12:15]
	v_mfma_f32_16x16x32_bf16 v[4:7], v[166:169], v[202:205], v[4:7]
	s_setprio 0
	s_barrier
	s_add_u32 s54, s24, 0x80000
	s_addc_u32 s55, s25, 0
	s_add_i32 s53, s45, s34
	v_lshl_add_u64 v[150:151], s[54:55], 0, v[130:131]
	s_mov_b32 m0, s53
	s_nop 0
	global_load_lds_dwordx4 v[150:151], off
	v_lshl_add_u64 v[150:151], s[54:55], 0, v[134:135]
	s_add_i32 m0, s53, 0x2000
	s_nop 0
	global_load_lds_dwordx4 v[150:151], off
	ds_read_b128 v[150:153], v147 offset:32768
	ds_read_b128 v[154:157], v147 offset:33792
	ds_read_b128 v[162:165], v147 offset:34816
	ds_read_b128 v[166:169], v147 offset:35840
	s_waitcnt vmcnt(6)
	s_barrier
	s_setprio 1
	v_mfma_f32_16x16x32_bf16 v[56:59], v[206:209], v[170:173], v[56:59]
	v_mfma_f32_16x16x32_bf16 v[48:51], v[214:217], v[170:173], v[48:51]
	v_mfma_f32_16x16x32_bf16 v[40:43], v[206:209], v[178:181], v[40:43]
	v_mfma_f32_16x16x32_bf16 v[32:35], v[214:217], v[178:181], v[32:35]
	v_mfma_f32_16x16x32_bf16 v[24:27], v[206:209], v[190:193], v[24:27]
	v_mfma_f32_16x16x32_bf16 v[16:19], v[214:217], v[190:193], v[16:19]
	v_mfma_f32_16x16x32_bf16 v[8:11], v[206:209], v[198:201], v[8:11]
	v_mfma_f32_16x16x32_bf16 v[0:3], v[214:217], v[198:201], v[0:3]
	v_mfma_f32_16x16x32_bf16 v[56:59], v[210:213], v[174:177], v[56:59]
	v_mfma_f32_16x16x32_bf16 v[48:51], v[218:221], v[174:177], v[48:51]
	v_mfma_f32_16x16x32_bf16 v[40:43], v[210:213], v[186:189], v[40:43]
	v_mfma_f32_16x16x32_bf16 v[32:35], v[218:221], v[186:189], v[32:35]
	v_mfma_f32_16x16x32_bf16 v[24:27], v[210:213], v[194:197], v[24:27]
	v_mfma_f32_16x16x32_bf16 v[16:19], v[218:221], v[194:197], v[16:19]
	v_mfma_f32_16x16x32_bf16 v[8:11], v[210:213], v[202:205], v[8:11]
	v_mfma_f32_16x16x32_bf16 v[0:3], v[218:221], v[202:205], v[0:3]
	s_setprio 0
	s_add_i32 s53, 0, 0x18000
	v_add_u32_e32 v161, s53, v145
	s_barrier
	s_add_u32 s26, s26, 0x80000
	s_addc_u32 s27, s27, 0
	s_mov_b32 m0, s38
	v_lshl_add_u64 v[206:207], s[26:27], 0, v[128:129]
	ds_read_b128 v[170:173], v148 offset:32768
	ds_read_b128 v[174:177], v148 offset:33792
	ds_read_b128 v[178:181], v148 offset:34816
	ds_read_b128 v[186:189], v148 offset:35840
	ds_read_b128 v[190:193], v148 offset:36864
	ds_read_b128 v[194:197], v148 offset:37888
	ds_read_b128 v[198:201], v148 offset:38912
	ds_read_b128 v[202:205], v148 offset:39936
	global_load_lds_dwordx4 v[206:207], off
	v_lshl_add_u64 v[206:207], s[26:27], 0, v[132:133]
	s_mov_b32 m0, s39
	s_nop 0
	global_load_lds_dwordx4 v[206:207], off
	s_waitcnt lgkmcnt(8)
	s_barrier
; #define PG8_STAGE(bufoff, gbase, voff) do { _Pragma("unroll") for (int _i = 0; _i < 2; ++_i) \
;         __builtin_amdgcn_global_load_lds((const unsigned*)((const char*)(gbase) + (voff)[_i]), (LAS unsigned*)(lds + (bufoff) + ldsw + _i * 8192), 16, 0, 0); } while (0)
; #define PG8_LDA(dst, b, h) do { _Pragma("unroll") for (int m = 0; m < 4; ++m) _Pragma("unroll") for (int k = 0; k < 2; ++k) dst[m][k] = *(const LAS bf16x8*)(lds + PG8_SA(b, h) + aoff + m * 2048 + k * 1024); } while (0)
; #define PG8_LDB(dst, b, h) do { _Pragma("unroll") for (int n = 0; n < 2; ++n) _Pragma("unroll") for (int k = 0; k < 2; ++k) dst[n][k] = *(const LAS bf16x8*)(lds + PG8_SB(b, h) + boff + n * 2048 + k * 1024); } while (0)
; #define PG8_MMA(ai, bj, At, Bt) do { __builtin_amdgcn_s_setprio(1); _Pragma("unroll") for (int m = 0; m < 4; ++m) _Pragma("unroll") for (int n = 0; n < 2; ++n) _Pragma("unroll") for (int k = 0; k < 2; ++k) \
;         acc[ai][bj][m][n] = __builtin_amdgcn_mfma_f32_16x16x32_bf16(Bt[n][k], At[m][k], acc[ai][bj][m][n], 0, 0, 0); __builtin_amdgcn_s_setprio(0); } while (0)
; #define PG8_WAIT_L(n) asm volatile("s_waitcnt lgkmcnt(" #n ")" ::: "memory")
; #define PG8_BAR __builtin_amdgcn_s_barrier()
; #define PG8_SCHED __builtin_amdgcn_sched_barrier(0)
; template <class Epi, class Sched>
; __device__ __forceinline__ void gemm_phase(LAS unsigned char* lds, const Gemm g, const Sched& S, const Epi& E) {
;     ...
;             PG8_WAIT_L(8); PG8_BAR; PG8_WAIT_L(0); PG8_MMA(0, 0, At, B0); PG8_BAR; PG8_SCHED;
;             PG8_LDB(B1, 1, 1); PG8_STAGE(PG8_SB(1, 0), b3, voffB);
;             PG8_BAR; PG8_WAIT_L(0); if constexpr (!Epi::DIAG) PG8_MMA(0, 1, At, B1); PG8_BAR;
;             PG8_LDA(At, 1, 1); PG8_STAGE(PG8_SA(1, 0), a3, voffA);
;             PG8_BAR; PG8_WAIT_L(0); if constexpr (!Epi::DIAG) PG8_MMA(1, 0, At, B0); PG8_BAR; PG8_SCHED;
;             PG8_STAGE(PG8_SB(1, 1), b3 + hstepB, voffB);
	s_waitcnt lgkmcnt(0)
	s_setprio 1
	s_waitcnt lgkmcnt(0)
	v_mfma_f32_16x16x32_bf16 v[124:127], v[150:153], v[170:173], v[124:127]
	v_mfma_f32_16x16x32_bf16 v[116:119], v[162:165], v[170:173], v[116:119]
	v_mfma_f32_16x16x32_bf16 v[108:111], v[150:153], v[178:181], v[108:111]
	v_mfma_f32_16x16x32_bf16 v[100:103], v[162:165], v[178:181], v[100:103]
	v_mfma_f32_16x16x32_bf16 v[92:95], v[150:153], v[190:193], v[92:95]
	v_mfma_f32_16x16x32_bf16 v[84:87], v[162:165], v[190:193], v[84:87]
	v_mfma_f32_16x16x32_bf16 v[76:79], v[150:153], v[198:201], v[76:79]
	v_mfma_f32_16x16x32_bf16 v[68:71], v[162:165], v[198:201], v[68:71]
	v_mfma_f32_16x16x32_bf16 v[124:127], v[154:157], v[174:177], v[124:127]
	v_mfma_f32_16x16x32_bf16 v[116:119], v[166:169], v[174:177], v[116:119]
	v_mfma_f32_16x16x32_bf16 v[108:111], v[154:157], v[186:189], v[108:111]
	v_mfma_f32_16x16x32_bf16 v[100:103], v[166:169], v[186:189], v[100:103]
	v_mfma_f32_16x16x32_bf16 v[92:95], v[154:157], v[194:197], v[92:95]
	v_mfma_f32_16x16x32_bf16 v[84:87], v[166:169], v[194:197], v[84:87]
	v_mfma_f32_16x16x32_bf16 v[76:79], v[154:157], v[202:205], v[76:79]
	v_mfma_f32_16x16x32_bf16 v[68:71], v[166:169], v[202:205], v[68:71]
	s_setprio 0
	s_barrier
	s_add_i32 s26, 0, 0x1c000
	s_add_i32 s27, s53, s34
	v_add_u32_e32 v161, s26, v145
	v_lshl_add_u64 v[158:159], v[158:159], 0, s[10:11]
	s_mov_b32 m0, s27
	ds_read_b128 v[206:209], v161
	ds_read_b128 v[210:213], v161 offset:1024
	ds_read_b128 v[214:217], v161 offset:2048
	ds_read_b128 v[218:221], v161 offset:3072
	global_load_lds_dwordx4 v[158:159], off
	v_lshl_add_u64 v[158:159], v[182:183], 0, s[10:11]
	s_add_i32 m0, s27, 0x2000
	s_nop 0
	global_load_lds_dwordx4 v[158:159], off
	s_barrier
	s_waitcnt lgkmcnt(0)
	s_setprio 1
	s_waitcnt lgkmcnt(0)
	v_mfma_f32_16x16x32_bf16 v[120:123], v[206:209], v[170:173], v[120:123]
	v_mfma_f32_16x16x32_bf16 v[112:115], v[214:217], v[170:173], v[112:115]
	v_mfma_f32_16x16x32_bf16 v[104:107], v[206:209], v[178:181], v[104:107]
	v_mfma_f32_16x16x32_bf16 v[96:99], v[214:217], v[178:181], v[96:99]
	v_mfma_f32_16x16x32_bf16 v[88:91], v[206:209], v[190:193], v[88:91]
	v_mfma_f32_16x16x32_bf16 v[80:83], v[214:217], v[190:193], v[80:83]
	v_mfma_f32_16x16x32_bf16 v[72:75], v[206:209], v[198:201], v[72:75]
	v_mfma_f32_16x16x32_bf16 v[64:67], v[214:217], v[198:201], v[64:67]
	v_mfma_f32_16x16x32_bf16 v[120:123], v[210:213], v[174:177], v[120:123]
	v_mfma_f32_16x16x32_bf16 v[112:115], v[218:221], v[174:177], v[112:115]
	v_mfma_f32_16x16x32_bf16 v[104:107], v[210:213], v[186:189], v[104:107]
	v_mfma_f32_16x16x32_bf16 v[96:99], v[218:221], v[186:189], v[96:99]
	v_mfma_f32_16x16x32_bf16 v[88:91], v[210:213], v[194:197], v[88:91]
	v_mfma_f32_16x16x32_bf16 v[80:83], v[218:221], v[194:197], v[80:83]
	v_mfma_f32_16x16x32_bf16 v[72:75], v[210:213], v[202:205], v[72:75]
	v_mfma_f32_16x16x32_bf16 v[64:67], v[218:221], v[202:205], v[64:67]
	s_setprio 0
	s_mov_b32 m0, s42
	v_lshl_add_u64 v[158:159], v[222:223], 0, s[10:11]
	s_barrier
	ds_read_b128 v[170:173], v148 offset:49152
	ds_read_b128 v[174:177], v148 offset:50176
	ds_read_b128 v[178:181], v148 offset:51200
	ds_read_b128 v[186:189], v148 offset:52224
	ds_read_b128 v[190:193], v148 offset:53248
	ds_read_b128 v[194:197], v148 offset:54272
	ds_read_b128 v[198:201], v148 offset:55296
	ds_read_b128 v[202:205], v148 offset:56320
	global_load_lds_dwordx4 v[158:159], off
	v_lshl_add_u64 v[158:159], v[224:225], 0, s[10:11]
	s_mov_b32 m0, s43
	s_nop 0
	global_load_lds_dwordx4 v[158:159], off
	s_waitcnt vmcnt(10)
	s_barrier
	s_waitcnt lgkmcnt(0)
	s_setprio 1
	s_waitcnt lgkmcnt(0)
	v_mfma_f32_16x16x32_bf16 v[60:63], v[150:153], v[170:173], v[60:63]
	v_mfma_f32_16x16x32_bf16 v[52:55], v[162:165], v[170:173], v[52:55]
	v_mfma_f32_16x16x32_bf16 v[44:47], v[150:153], v[178:181], v[44:47]
	v_mfma_f32_16x16x32_bf16 v[36:39], v[162:165], v[178:181], v[36:39]
	v_mfma_f32_16x16x32_bf16 v[28:31], v[150:153], v[190:193], v[28:31]
	v_mfma_f32_16x16x32_bf16 v[20:23], v[162:165], v[190:193], v[20:23]
	v_mfma_f32_16x16x32_bf16 v[12:15], v[150:153], v[198:201], v[12:15]
	v_mfma_f32_16x16x32_bf16 v[4:7], v[162:165], v[198:201], v[4:7]
	v_mfma_f32_16x16x32_bf16 v[60:63], v[154:157], v[174:177], v[60:63]
	v_mfma_f32_16x16x32_bf16 v[52:55], v[166:169], v[174:177], v[52:55]
	v_mfma_f32_16x16x32_bf16 v[44:47], v[154:157], v[186:189], v[44:47]
	v_mfma_f32_16x16x32_bf16 v[36:39], v[166:169], v[186:189], v[36:39]
	v_mfma_f32_16x16x32_bf16 v[28:31], v[154:157], v[194:197], v[28:31]
	v_mfma_f32_16x16x32_bf16 v[20:23], v[166:169], v[194:197], v[20:23]
	v_mfma_f32_16x16x32_bf16 v[12:15], v[154:157], v[202:205], v[12:15]
	v_mfma_f32_16x16x32_bf16 v[4:7], v[166:169], v[202:205], v[4:7]
	s_setprio 0
	s_barrier
	s_add_u32 s24, s24, 0x80080
	s_addc_u32 s25, s25, 0
	s_add_i32 s26, s26, s34
	v_lshl_add_u64 v[150:151], s[24:25], 0, v[130:131]
	s_mov_b32 m0, s26
	s_nop 0
	global_load_lds_dwordx4 v[150:151], off
	v_lshl_add_u64 v[150:151], s[24:25], 0, v[134:135]
	s_add_i32 m0, s26, 0x2000
	s_nop 0
	global_load_lds_dwordx4 v[150:151], off
	ds_read_b128 v[150:153], v147
	ds_read_b128 v[154:157], v147 offset:1024
	ds_read_b128 v[162:165], v147 offset:2048
	ds_read_b128 v[166:169], v147 offset:3072
	s_waitcnt vmcnt(6)
	s_barrier
; __device__ __forceinline__ u32x4 pack8(const float* f) { u32x4 w; w.x = pk2(f[0], f[1]); w.y = pk2(f[2], f[3]); w.z = pk2(f[4], f[5]); w.w = pk2(f[6], f[7]); return w; }
; #define PG8_STAGE(bufoff, gbase, voff) do { _Pragma("unroll") for (int _i = 0; _i < 2; ++_i) \
;         __builtin_amdgcn_global_load_lds((const unsigned*)((const char*)(gbase) + (voff)[_i]), (LAS unsigned*)(lds + (bufoff) + ldsw + _i * 8192), 16, 0, 0); } while (0)
; #define PG8_MMA(ai, bj, At, Bt) do { __builtin_amdgcn_s_setprio(1); _Pragma("unroll") for (int m = 0; m < 4; ++m) _Pragma("unroll") for (int n = 0; n < 2; ++n) _Pragma("unroll") for (int k = 0; k < 2; ++k) \
;         acc[ai][bj][m][n] = __builtin_amdgcn_mfma_f32_16x16x32_bf16(Bt[n][k], At[m][k], acc[ai][bj][m][n], 0, 0, 0); __builtin_amdgcn_s_setprio(0); } while (0)
; #define PG8_WAIT_V(n) asm volatile("s_waitcnt vmcnt(" #n ")" ::: "memory")
; #define PG8_BAR __builtin_amdgcn_s_barrier()
; template <class Epi, class Sched>
; __device__ __forceinline__ void gemm_phase(LAS unsigned char* lds, const Gemm g, const Sched& S, const Epi& E) {
;     ...
;             PG8_STAGE(PG8_SB(1, 1), b3 + hstepB, voffB);
;             PG8_WAIT_V(6); PG8_BAR; PG8_MMA(1, 1, At, B1); PG8_BAR;
;         }
;     __device__ __forceinline__ void operator()(const Acc& acc, const Unit& u, int wr, int wc, int fr, int fq) const {
;         const int row0 = u.pm * BM + wr * 64 + fr, col0 = u.pn * HALF + wc * 32 + 8 * fq;
; #pragma unroll
;         for (int ai = 0; ai < 2; ++ai)
; #pragma unroll
;             for (int m = 0; m < 4; ++m) { float v[8];
; #pragma unroll
;                 for (int n = 0; n < 2; ++n) {
;                     const f32x4 gt = acc[ai][0][m][n], arg = gt * (-1.4426950408889634f), gu = gt * acc[ai][1][m][n];
;                     f32x4 t;
; #pragma unroll
;                     for (int j = 0; j < 4; ++j) t[j] = __builtin_amdgcn_exp2f(arg[j]);
;                     t = t + 1.0f;
; #pragma unroll
;                     for (int j = 0; j < 4; ++j) t[j] = __builtin_amdgcn_rcpf(t[j]);
;                     const f32x4 r = gu * t;
; #pragma unroll
;                     for (int j = 0; j < 4; ++j) v[4 * n + j] = r[j]; }
;                 *(u32x4*)(O + (size_t)(row0 + ai * HALF + m * 16) * DFF + col0) = pack8(v); }
	s_setprio 1
	v_mfma_f32_16x16x32_bf16 v[56:59], v[206:209], v[170:173], v[56:59]
	v_mfma_f32_16x16x32_bf16 v[48:51], v[214:217], v[170:173], v[48:51]
	v_mfma_f32_16x16x32_bf16 v[40:43], v[206:209], v[178:181], v[40:43]
	v_mfma_f32_16x16x32_bf16 v[32:35], v[214:217], v[178:181], v[32:35]
	v_mfma_f32_16x16x32_bf16 v[24:27], v[206:209], v[190:193], v[24:27]
	v_mfma_f32_16x16x32_bf16 v[16:19], v[214:217], v[190:193], v[16:19]
	v_mfma_f32_16x16x32_bf16 v[8:11], v[206:209], v[198:201], v[8:11]
	v_mfma_f32_16x16x32_bf16 v[0:3], v[214:217], v[198:201], v[0:3]
	v_mfma_f32_16x16x32_bf16 v[56:59], v[210:213], v[174:177], v[56:59]
	v_mfma_f32_16x16x32_bf16 v[48:51], v[218:221], v[174:177], v[48:51]
	v_mfma_f32_16x16x32_bf16 v[40:43], v[210:213], v[186:189], v[40:43]
	v_mfma_f32_16x16x32_bf16 v[32:35], v[218:221], v[186:189], v[32:35]
	v_mfma_f32_16x16x32_bf16 v[24:27], v[210:213], v[194:197], v[24:27]
	v_mfma_f32_16x16x32_bf16 v[16:19], v[218:221], v[194:197], v[16:19]
	v_mfma_f32_16x16x32_bf16 v[8:11], v[210:213], v[202:205], v[8:11]
	v_mfma_f32_16x16x32_bf16 v[0:3], v[218:221], v[202:205], v[0:3]
	s_setprio 0
	s_add_i32 s52, s52, 2
	s_add_u32 s22, s22, 0x100
	s_addc_u32 s23, s23, 0
	s_add_u32 s50, s50, 0x100
	s_addc_u32 s51, s51, 0
	s_cmp_gt_u32 s52, 29
	s_barrier
	s_cbranch_scc0 .LBB0_1843
	v_mul_f32_e32 v153, 0xbfb8aa3b, v126
	v_exp_f32_e32 v154, v153
	v_mul_f32_e32 v153, 0xbfb8aa3b, v127
	v_mul_f32_e32 v151, 0xbfb8aa3b, v124
	v_exp_f32_e32 v155, v153
	v_exp_f32_e32 v152, v151
	v_mul_f32_e32 v151, 0xbfb8aa3b, v125
	v_pk_mul_f32 v[120:121], v[120:121], v[124:125]
	v_mul_f32_e32 v124, 0xbfb8aa3b, v116
	v_mul_f32_e32 v125, 0xbfb8aa3b, v117
	v_pk_mul_f32 v[122:123], v[122:123], v[126:127]
	v_exp_f32_e32 v124, v124
	v_mul_f32_e32 v126, 0xbfb8aa3b, v118
	v_mul_f32_e32 v127, 0xbfb8aa3b, v119
	v_exp_f32_e32 v125, v125
	v_exp_f32_e32 v153, v151
	v_exp_f32_e32 v126, v126
	v_exp_f32_e32 v127, v127
	v_pk_add_f32 v[154:155], v[154:155], 1.0 op_sel_hi:[1,0]
	v_pk_add_f32 v[124:125], v[124:125], 1.0 op_sel_hi:[1,0]
	v_rcp_f32_e32 v154, v154
	v_rcp_f32_e32 v155, v155
	v_pk_add_f32 v[152:153], v[152:153], 1.0 op_sel_hi:[1,0]
	v_pk_add_f32 v[126:127], v[126:127], 1.0 op_sel_hi:[1,0]
	v_rcp_f32_e32 v124, v124
	v_rcp_f32_e32 v125, v125
	v_rcp_f32_e32 v152, v152
	v_rcp_f32_e32 v153, v153
	v_rcp_f32_e32 v126, v126
	v_rcp_f32_e32 v127, v127
	v_pk_mul_f32 v[122:123], v[122:123], v[154:155]
	v_pk_mul_f32 v[112:113], v[112:113], v[116:117]
	v_cvt_pk_bf16_f32 v117, v122, v123
	v_mul_f32_e32 v122, 0xbfb8aa3b, v108
	v_mul_f32_e32 v123, 0xbfb8aa3b, v109
	v_lshl_or_b32 v156, s47, 7, v146
	v_pk_mul_f32 v[114:115], v[114:115], v[118:119]
	v_pk_mul_f32 v[112:113], v[112:113], v[124:125]
	v_exp_f32_e32 v122, v122
	v_mul_f32_e32 v124, 0xbfb8aa3b, v110
	v_mul_f32_e32 v125, 0xbfb8aa3b, v111
	v_exp_f32_e32 v123, v123
	v_pk_mul_f32 v[106:107], v[106:107], v[110:111]
	v_pk_mul_f32 v[104:105], v[104:105], v[108:109]
	v_mul_f32_e32 v108, 0xbfb8aa3b, v100
	v_mul_f32_e32 v109, 0xbfb8aa3b, v101
	v_mul_f32_e32 v110, 0xbfb8aa3b, v102
	v_mul_f32_e32 v111, 0xbfb8aa3b, v103
	v_lshl_add_u32 v150, s20, 8, v144
	v_ashrrev_i32_e32 v157, 31, v156
	v_pk_mul_f32 v[120:121], v[120:121], v[152:153]
	v_pk_mul_f32 v[114:115], v[114:115], v[126:127]
	v_cvt_pk_bf16_f32 v118, v112, v113
	v_mov_b64_e32 v[112:113], s[8:9]
	v_exp_f32_e32 v108, v108
	v_exp_f32_e32 v110, v110
	v_exp_f32_e32 v111, v111
	v_exp_f32_e32 v109, v109
	v_cvt_pk_bf16_f32 v116, v120, v121
	v_cvt_pk_bf16_f32 v119, v114, v115
	v_mad_i64_i32 v[120:121], s[22:23], v150, s46, v[112:113]
	v_lshlrev_b64 v[114:115], 1, v[156:157]
	v_lshl_add_u64 v[120:121], v[120:121], 0, v[114:115]
	global_store_dwordx4 v[120:121], v[116:119], off
	v_exp_f32_e32 v124, v124
	v_exp_f32_e32 v125, v125
	v_pk_add_f32 v[118:119], v[122:123], 1.0 op_sel_hi:[1,0]
	v_pk_add_f32 v[110:111], v[110:111], 1.0 op_sel_hi:[1,0]
	v_rcp_f32_e32 v118, v118
	v_rcp_f32_e32 v119, v119
	v_pk_add_f32 v[108:109], v[108:109], 1.0 op_sel_hi:[1,0]
	v_rcp_f32_e32 v110, v110
	v_rcp_f32_e32 v108, v108
	v_rcp_f32_e32 v109, v109
	v_rcp_f32_e32 v111, v111
	v_pk_add_f32 v[116:117], v[124:125], 1.0 op_sel_hi:[1,0]
	v_pk_mul_f32 v[104:105], v[104:105], v[118:119]
	v_pk_mul_f32 v[98:99], v[98:99], v[102:103]
	v_pk_mul_f32 v[96:97], v[96:97], v[100:101]
	v_rcp_f32_e32 v116, v116
	v_rcp_f32_e32 v117, v117
	v_pk_mul_f32 v[100:101], v[96:97], v[108:109]
	v_pk_mul_f32 v[102:103], v[98:99], v[110:111]
	v_cvt_pk_bf16_f32 v96, v104, v105
	v_mul_f32_e32 v104, 0xbfb8aa3b, v94
	v_mul_f32_e32 v105, 0xbfb8aa3b, v95
	v_pk_mul_f32 v[90:91], v[90:91], v[94:95]
	v_mul_f32_e32 v94, 0xbfb8aa3b, v86
	v_mul_f32_e32 v95, 0xbfb8aa3b, v87
	v_cvt_pk_bf16_f32 v99, v102, v103
	v_mul_f32_e32 v102, 0xbfb8aa3b, v92
	v_mul_f32_e32 v103, 0xbfb8aa3b, v93
	v_exp_f32_e32 v94, v94
	v_exp_f32_e32 v95, v95
	v_exp_f32_e32 v102, v102
	v_exp_f32_e32 v103, v103
	v_pk_mul_f32 v[88:89], v[88:89], v[92:93]
	v_mul_f32_e32 v92, 0xbfb8aa3b, v84
	v_mul_f32_e32 v93, 0xbfb8aa3b, v85
	v_cvt_pk_bf16_f32 v98, v100, v101
	v_or_b32_e32 v100, 16, v150
	v_exp_f32_e32 v92, v92
	v_exp_f32_e32 v93, v93
	v_pk_mul_f32 v[106:107], v[106:107], v[116:117]
	v_mad_i64_i32 v[100:101], s[22:23], v100, s46, v[112:113]
	v_cvt_pk_bf16_f32 v97, v106, v107
	v_exp_f32_e32 v104, v104
	v_exp_f32_e32 v105, v105
	v_lshl_add_u64 v[100:101], v[100:101], 0, v[114:115]
	v_pk_add_f32 v[94:95], v[94:95], 1.0 op_sel_hi:[1,0]
	global_store_dwordx4 v[100:101], v[96:99], off
	v_rcp_f32_e32 v94, v94
	v_rcp_f32_e32 v95, v95
	v_pk_add_f32 v[98:99], v[102:103], 1.0 op_sel_hi:[1,0]
	v_pk_add_f32 v[92:93], v[92:93], 1.0 op_sel_hi:[1,0]
	v_rcp_f32_e32 v98, v98
	v_rcp_f32_e32 v99, v99
; __device__ __forceinline__ u32x4 pack8(const float* f) { u32x4 w; w.x = pk2(f[0], f[1]); w.y = pk2(f[2], f[3]); w.z = pk2(f[4], f[5]); w.w = pk2(f[6], f[7]); return w; }
;     __device__ __forceinline__ void operator()(const Acc& acc, const Unit& u, int wr, int wc, int fr, int fq) const {
;     ...
; #pragma unroll
;         for (int ai = 0; ai < 2; ++ai)
; #pragma unroll
;             for (int m = 0; m < 4; ++m) { float v[8];
; #pragma unroll
;                 for (int n = 0; n < 2; ++n) {
;                     const f32x4 gt = acc[ai][0][m][n], arg = gt * (-1.4426950408889634f), gu = gt * acc[ai][1][m][n];
;                     f32x4 t;
; #pragma unroll
;                     for (int j = 0; j < 4; ++j) t[j] = __builtin_amdgcn_exp2f(arg[j]);
;                     t = t + 1.0f;
; #pragma unroll
;                     for (int j = 0; j < 4; ++j) t[j] = __builtin_amdgcn_rcpf(t[j]);
;                     const f32x4 r = gu * t;
; #pragma unroll
;                     for (int j = 0; j < 4; ++j) v[4 * n + j] = r[j]; }
;                 *(u32x4*)(O + (size_t)(row0 + ai * HALF + m * 16) * DFF + col0) = pack8(v); }
	v_rcp_f32_e32 v92, v92
	v_rcp_f32_e32 v93, v93
	v_pk_add_f32 v[96:97], v[104:105], 1.0 op_sel_hi:[1,0]
	v_pk_mul_f32 v[82:83], v[82:83], v[86:87]
	v_rcp_f32_e32 v96, v96
	v_rcp_f32_e32 v97, v97
	v_pk_mul_f32 v[86:87], v[82:83], v[94:95]
	v_pk_mul_f32 v[88:89], v[88:89], v[98:99]
	v_pk_mul_f32 v[80:81], v[80:81], v[84:85]
	v_cvt_pk_bf16_f32 v83, v86, v87
	v_mul_f32_e32 v86, 0xbfb8aa3b, v76
	v_mul_f32_e32 v87, 0xbfb8aa3b, v77
	v_pk_mul_f32 v[84:85], v[80:81], v[92:93]
	v_cvt_pk_bf16_f32 v80, v88, v89
	v_exp_f32_e32 v86, v86
	v_mul_f32_e32 v88, 0xbfb8aa3b, v78
	v_mul_f32_e32 v89, 0xbfb8aa3b, v79
	v_exp_f32_e32 v87, v87
	v_pk_mul_f32 v[74:75], v[74:75], v[78:79]
	v_pk_mul_f32 v[72:73], v[72:73], v[76:77]
	v_mul_f32_e32 v76, 0xbfb8aa3b, v68
	v_mul_f32_e32 v77, 0xbfb8aa3b, v69
	v_mul_f32_e32 v78, 0xbfb8aa3b, v70
	v_mul_f32_e32 v79, 0xbfb8aa3b, v71
	v_cvt_pk_bf16_f32 v82, v84, v85
	v_or_b32_e32 v84, 32, v150
	v_exp_f32_e32 v76, v76
	v_exp_f32_e32 v78, v78
	v_exp_f32_e32 v79, v79
	v_exp_f32_e32 v77, v77
	v_pk_mul_f32 v[90:91], v[90:91], v[96:97]
	v_mad_i64_i32 v[84:85], s[22:23], v84, s46, v[112:113]
	v_cvt_pk_bf16_f32 v81, v90, v91
	v_lshl_add_u64 v[84:85], v[84:85], 0, v[114:115]
	global_store_dwordx4 v[84:85], v[80:83], off
	v_exp_f32_e32 v88, v88
	v_exp_f32_e32 v89, v89
	v_pk_add_f32 v[82:83], v[86:87], 1.0 op_sel_hi:[1,0]
	v_pk_add_f32 v[78:79], v[78:79], 1.0 op_sel_hi:[1,0]
	v_rcp_f32_e32 v82, v82
	v_rcp_f32_e32 v83, v83
	v_pk_add_f32 v[76:77], v[76:77], 1.0 op_sel_hi:[1,0]
	v_rcp_f32_e32 v78, v78
	v_rcp_f32_e32 v76, v76
	v_rcp_f32_e32 v77, v77
	v_rcp_f32_e32 v79, v79
	v_pk_add_f32 v[80:81], v[88:89], 1.0 op_sel_hi:[1,0]
	v_pk_mul_f32 v[72:73], v[72:73], v[82:83]
	v_pk_mul_f32 v[66:67], v[66:67], v[70:71]
	v_pk_mul_f32 v[64:65], v[64:65], v[68:69]
	v_rcp_f32_e32 v80, v80
	v_rcp_f32_e32 v81, v81
	v_pk_mul_f32 v[68:69], v[64:65], v[76:77]
	v_pk_mul_f32 v[70:71], v[66:67], v[78:79]
	v_cvt_pk_bf16_f32 v64, v72, v73
	v_mul_f32_e32 v72, 0xbfb8aa3b, v62
	v_mul_f32_e32 v73, 0xbfb8aa3b, v63
	v_pk_mul_f32 v[58:59], v[58:59], v[62:63]
	v_mul_f32_e32 v62, 0xbfb8aa3b, v54
	v_mul_f32_e32 v63, 0xbfb8aa3b, v55
	v_cvt_pk_bf16_f32 v67, v70, v71
	v_mul_f32_e32 v70, 0xbfb8aa3b, v60
	v_mul_f32_e32 v71, 0xbfb8aa3b, v61
	v_exp_f32_e32 v62, v62
	v_exp_f32_e32 v63, v63
	v_exp_f32_e32 v70, v70
	v_exp_f32_e32 v71, v71
	v_pk_mul_f32 v[56:57], v[56:57], v[60:61]
	v_mul_f32_e32 v60, 0xbfb8aa3b, v52
	v_mul_f32_e32 v61, 0xbfb8aa3b, v53
	v_cvt_pk_bf16_f32 v66, v68, v69
	v_or_b32_e32 v68, 48, v150
	v_exp_f32_e32 v60, v60
	v_exp_f32_e32 v61, v61
	v_pk_mul_f32 v[74:75], v[74:75], v[80:81]
	v_mad_i64_i32 v[68:69], s[22:23], v68, s46, v[112:113]
	v_cvt_pk_bf16_f32 v65, v74, v75
	v_lshl_add_u64 v[68:69], v[68:69], 0, v[114:115]
	v_exp_f32_e32 v72, v72
	v_exp_f32_e32 v73, v73
	v_pk_add_f32 v[62:63], v[62:63], 1.0 op_sel_hi:[1,0]
	global_store_dwordx4 v[68:69], v[64:67], off
	v_rcp_f32_e32 v62, v62
	v_rcp_f32_e32 v63, v63
	v_pk_add_f32 v[66:67], v[70:71], 1.0 op_sel_hi:[1,0]
	v_pk_add_f32 v[60:61], v[60:61], 1.0 op_sel_hi:[1,0]
	v_rcp_f32_e32 v66, v66
	v_rcp_f32_e32 v67, v67
	v_rcp_f32_e32 v60, v60
	v_rcp_f32_e32 v61, v61
	v_pk_add_f32 v[64:65], v[72:73], 1.0 op_sel_hi:[1,0]
	v_pk_mul_f32 v[50:51], v[50:51], v[54:55]
	v_rcp_f32_e32 v64, v64
	v_rcp_f32_e32 v65, v65
	v_pk_mul_f32 v[54:55], v[50:51], v[62:63]
	v_pk_mul_f32 v[56:57], v[56:57], v[66:67]
	v_pk_mul_f32 v[48:49], v[48:49], v[52:53]
	v_cvt_pk_bf16_f32 v51, v54, v55
	v_mul_f32_e32 v54, 0xbfb8aa3b, v44
	v_mul_f32_e32 v55, 0xbfb8aa3b, v45
	v_pk_mul_f32 v[52:53], v[48:49], v[60:61]
	v_cvt_pk_bf16_f32 v48, v56, v57
	v_exp_f32_e32 v54, v54
	v_mul_f32_e32 v56, 0xbfb8aa3b, v46
	v_mul_f32_e32 v57, 0xbfb8aa3b, v47
	v_exp_f32_e32 v55, v55
	v_pk_mul_f32 v[42:43], v[42:43], v[46:47]
	v_pk_mul_f32 v[40:41], v[40:41], v[44:45]
	v_mul_f32_e32 v44, 0xbfb8aa3b, v36
	v_mul_f32_e32 v45, 0xbfb8aa3b, v37
	v_mul_f32_e32 v46, 0xbfb8aa3b, v38
	v_mul_f32_e32 v47, 0xbfb8aa3b, v39
	v_add_u32_e32 v68, 0x80, v150
	v_exp_f32_e32 v44, v44
	v_exp_f32_e32 v46, v46
	v_exp_f32_e32 v47, v47
	v_exp_f32_e32 v45, v45
	v_pk_mul_f32 v[58:59], v[58:59], v[64:65]
	v_cvt_pk_bf16_f32 v50, v52, v53
	v_mad_i64_i32 v[52:53], s[22:23], v68, s46, v[112:113]
	v_cvt_pk_bf16_f32 v49, v58, v59
	v_lshl_add_u64 v[52:53], v[52:53], 0, v[114:115]
	global_store_dwordx4 v[52:53], v[48:51], off
; __device__ __forceinline__ u32x4 pack8(const float* f) { u32x4 w; w.x = pk2(f[0], f[1]); w.y = pk2(f[2], f[3]); w.z = pk2(f[4], f[5]); w.w = pk2(f[6], f[7]); return w; }
; #define PG8_WAIT_V(n) asm volatile("s_waitcnt vmcnt(" #n ")" ::: "memory")
; #define PG8_BAR __builtin_amdgcn_s_barrier()
; template <class Epi, class Sched>
; __device__ __forceinline__ void gemm_phase(LAS unsigned char* lds, const Gemm g, const Sched& S, const Epi& E) {
;     ...
;         cur = nxt; cA = nA; cB = nB; ++ui;
;     }
;     PG8_WAIT_V(0);
;     if (wr == 0) PG8_BAR;
;     PG8_BAR;
;     __device__ __forceinline__ void operator()(const Acc& acc, const Unit& u, int wr, int wc, int fr, int fq) const {
;     ...
; #pragma unroll
;         for (int ai = 0; ai < 2; ++ai)
; #pragma unroll
;             for (int m = 0; m < 4; ++m) { float v[8];
; #pragma unroll
;                 for (int n = 0; n < 2; ++n) {
;                     const f32x4 gt = acc[ai][0][m][n], arg = gt * (-1.4426950408889634f), gu = gt * acc[ai][1][m][n];
;                     f32x4 t;
; #pragma unroll
;                     for (int j = 0; j < 4; ++j) t[j] = __builtin_amdgcn_exp2f(arg[j]);
;                     t = t + 1.0f;
; #pragma unroll
;                     for (int j = 0; j < 4; ++j) t[j] = __builtin_amdgcn_rcpf(t[j]);
;                     const f32x4 r = gu * t;
; #pragma unroll
;                     for (int j = 0; j < 4; ++j) v[4 * n + j] = r[j]; }
;                 *(u32x4*)(O + (size_t)(row0 + ai * HALF + m * 16) * DFF + col0) = pack8(v); }
	v_exp_f32_e32 v56, v56
	v_exp_f32_e32 v57, v57
	v_pk_add_f32 v[50:51], v[54:55], 1.0 op_sel_hi:[1,0]
	v_pk_add_f32 v[46:47], v[46:47], 1.0 op_sel_hi:[1,0]
	v_rcp_f32_e32 v50, v50
	v_rcp_f32_e32 v51, v51
	v_pk_add_f32 v[44:45], v[44:45], 1.0 op_sel_hi:[1,0]
	v_rcp_f32_e32 v46, v46
	v_rcp_f32_e32 v44, v44
	v_rcp_f32_e32 v45, v45
	v_rcp_f32_e32 v47, v47
	v_pk_add_f32 v[48:49], v[56:57], 1.0 op_sel_hi:[1,0]
	v_pk_mul_f32 v[40:41], v[40:41], v[50:51]
	v_pk_mul_f32 v[34:35], v[34:35], v[38:39]
	v_pk_mul_f32 v[32:33], v[32:33], v[36:37]
	v_rcp_f32_e32 v48, v48
	v_rcp_f32_e32 v49, v49
	v_pk_mul_f32 v[36:37], v[32:33], v[44:45]
	v_pk_mul_f32 v[38:39], v[34:35], v[46:47]
	v_cvt_pk_bf16_f32 v32, v40, v41
	v_mul_f32_e32 v40, 0xbfb8aa3b, v30
	v_mul_f32_e32 v41, 0xbfb8aa3b, v31
	v_pk_mul_f32 v[26:27], v[26:27], v[30:31]
	v_mul_f32_e32 v30, 0xbfb8aa3b, v22
	v_mul_f32_e32 v31, 0xbfb8aa3b, v23
	v_cvt_pk_bf16_f32 v35, v38, v39
	v_mul_f32_e32 v38, 0xbfb8aa3b, v28
	v_mul_f32_e32 v39, 0xbfb8aa3b, v29
	v_exp_f32_e32 v30, v30
	v_exp_f32_e32 v31, v31
	v_exp_f32_e32 v38, v38
	v_exp_f32_e32 v39, v39
	v_pk_mul_f32 v[24:25], v[24:25], v[28:29]
	v_mul_f32_e32 v28, 0xbfb8aa3b, v20
	v_mul_f32_e32 v29, 0xbfb8aa3b, v21
	v_cvt_pk_bf16_f32 v34, v36, v37
	v_add_u32_e32 v36, 0x90, v150
	v_exp_f32_e32 v28, v28
	v_exp_f32_e32 v29, v29
	v_pk_mul_f32 v[42:43], v[42:43], v[48:49]
	v_mad_i64_i32 v[36:37], s[22:23], v36, s46, v[112:113]
	v_cvt_pk_bf16_f32 v33, v42, v43
	v_lshl_add_u64 v[36:37], v[36:37], 0, v[114:115]
	v_pk_add_f32 v[30:31], v[30:31], 1.0 op_sel_hi:[1,0]
	global_store_dwordx4 v[36:37], v[32:35], off
	v_rcp_f32_e32 v30, v30
	v_rcp_f32_e32 v31, v31
	v_pk_add_f32 v[34:35], v[38:39], 1.0 op_sel_hi:[1,0]
	v_exp_f32_e32 v40, v40
	v_exp_f32_e32 v41, v41
	v_rcp_f32_e32 v34, v34
	v_rcp_f32_e32 v35, v35
	v_pk_add_f32 v[28:29], v[28:29], 1.0 op_sel_hi:[1,0]
	v_pk_mul_f32 v[18:19], v[18:19], v[22:23]
	v_rcp_f32_e32 v28, v28
	v_rcp_f32_e32 v29, v29
	v_pk_mul_f32 v[22:23], v[18:19], v[30:31]
	v_pk_add_f32 v[32:33], v[40:41], 1.0 op_sel_hi:[1,0]
	v_pk_mul_f32 v[24:25], v[24:25], v[34:35]
	v_pk_mul_f32 v[16:17], v[16:17], v[20:21]
	v_cvt_pk_bf16_f32 v19, v22, v23
	v_mul_f32_e32 v22, 0xbfb8aa3b, v12
	v_mul_f32_e32 v23, 0xbfb8aa3b, v13
	v_pk_mul_f32 v[8:9], v[8:9], v[12:13]
	v_mul_f32_e32 v12, 0xbfb8aa3b, v4
	v_mul_f32_e32 v13, 0xbfb8aa3b, v5
	v_rcp_f32_e32 v32, v32
	v_rcp_f32_e32 v33, v33
	v_pk_mul_f32 v[20:21], v[16:17], v[28:29]
	v_cvt_pk_bf16_f32 v16, v24, v25
	v_mul_f32_e32 v24, 0xbfb8aa3b, v14
	v_mul_f32_e32 v25, 0xbfb8aa3b, v15
	v_pk_mul_f32 v[10:11], v[10:11], v[14:15]
	v_exp_f32_e32 v12, v12
	v_mul_f32_e32 v14, 0xbfb8aa3b, v6
	v_mul_f32_e32 v15, 0xbfb8aa3b, v7
	v_exp_f32_e32 v13, v13
	v_exp_f32_e32 v14, v14
	v_exp_f32_e32 v15, v15
	v_exp_f32_e32 v22, v22
	v_exp_f32_e32 v24, v24
	v_exp_f32_e32 v25, v25
	v_exp_f32_e32 v23, v23
	v_cvt_pk_bf16_f32 v18, v20, v21
	v_add_u32_e32 v20, 0xa0, v150
	v_pk_mul_f32 v[26:27], v[26:27], v[32:33]
	v_mad_i64_i32 v[20:21], s[22:23], v20, s46, v[112:113]
	v_pk_add_f32 v[12:13], v[12:13], 1.0 op_sel_hi:[1,0]
	v_cvt_pk_bf16_f32 v17, v26, v27
	v_lshl_add_u64 v[20:21], v[20:21], 0, v[114:115]
	v_pk_add_f32 v[14:15], v[14:15], 1.0 op_sel_hi:[1,0]
	v_rcp_f32_e32 v12, v12
	v_rcp_f32_e32 v13, v13
	global_store_dwordx4 v[20:21], v[16:19], off
	v_rcp_f32_e32 v14, v14
	v_rcp_f32_e32 v15, v15
	v_pk_add_f32 v[16:17], v[24:25], 1.0 op_sel_hi:[1,0]
	v_pk_add_f32 v[18:19], v[22:23], 1.0 op_sel_hi:[1,0]
	v_rcp_f32_e32 v16, v16
	v_rcp_f32_e32 v18, v18
	v_rcp_f32_e32 v19, v19
	v_rcp_f32_e32 v17, v17
	v_pk_mul_f32 v[0:1], v[0:1], v[4:5]
	v_pk_mul_f32 v[2:3], v[2:3], v[6:7]
	v_pk_mul_f32 v[4:5], v[0:1], v[12:13]
	v_pk_mul_f32 v[6:7], v[2:3], v[14:15]
	v_cvt_pk_bf16_f32 v2, v4, v5
	v_add_u32_e32 v4, 0xb0, v150
	v_pk_mul_f32 v[8:9], v[8:9], v[18:19]
	v_pk_mul_f32 v[10:11], v[10:11], v[16:17]
	v_mad_i64_i32 v[4:5], s[22:23], v4, s46, v[112:113]
	v_cvt_pk_bf16_f32 v0, v8, v9
	v_cvt_pk_bf16_f32 v1, v10, v11
	v_cvt_pk_bf16_f32 v3, v6, v7
	v_lshl_add_u64 v[4:5], v[4:5], 0, v[114:115]
	s_and_b64 vcc, exec, s[6:7]
	s_mov_b32 s47, s12
	s_mov_b32 s20, s14
	s_mov_b64 s[24:25], s[18:19]
	s_mov_b64 s[22:23], s[16:17]
	global_store_dwordx4 v[4:5], v[0:3], off
	s_cbranch_vccz .LBB0_1840
	s_waitcnt vmcnt(0)
	s_cmpk_gt_u32 s3, 0xff
	s_cbranch_scc1 .LBB0_1847
	s_barrier
